# MLA loop v2c: rescale-constant init moved to the rare rescale path, trimmed loop control SALU, merged both q-tile threshold checks, exp stream fully interleaved with QK MFMAs
# speedup vs baseline: 1.0217x; 1.0098x over previous
; #define LAS __attribute__((address_space(3)))
; #define ATT_BAR() asm volatile("s_waitcnt lgkmcnt(0)\n\ts_barrier" ::: "memory")
; template <int DQK> __device__ __forceinline__ void x1_tile(LAS unsigned char* lds, const bf16x8 (&qf)[2][DQK / 32], const float (&m)[2], f32x4 (&s)[2][4], int fr, int fq) {
;     constexpr int NKS = DQK / 32;
; #pragma unroll
;     for (int q = 0; q < 2; ++q) { const float c = (m[q] > -1e29f) ? -m[q] : 0.f;
; #pragma unroll
;         for (int ss = 0; ss < 4; ++ss) s[q][ss] = (f32x4){c, c, c, c}; }
; #pragma unroll
;     for (int ss = 0; ss < 4; ++ss)
; #pragma unroll
;         for (int ks = 0; ks < NKS; ++ks) {
;             const bf16x8 kf = *(const LAS bf16x8*)(lds + k_off<DQK>(16 * ss + fr, 4 * ks + fq));
; #pragma unroll
;             for (int q = 0; q < 2; ++q) s[q][ss] = __builtin_amdgcn_mfma_f32_16x16x32_bf16(kf, qf[q][ks], s[q][ss], 0, 0, 0);
;         }
; }
; template <int DQK> __device__ __forceinline__ void causal_pass_pipe(LAS unsigned char* lds, const bf16* K0, int p0, const bf16* K1, int p1, const bf16* V, int pv, int thi,
;         const bf16x8 (&qf)[2][DQK / 32], const int (&tpos)[2], int wave_tmin, int wave_tmax, f32x4 (&o)[2][4], int tid) {
;     asm volatile("" : "+v"(tid)); asm volatile("" : "+s"(K0), "+s"(V)); if (DQK == 96) asm volatile("" : "+s"(K1));
;     const int fr = tid & 15, fq = (tid & 63) >> 4;
;     constexpr int SLOT = KL<DQK>::SLOT;
;     float m[2] = {NEG, NEG}, l[2] = {0.f, 0.f};
; #pragma unroll
;     for (int i = 0; i < 2; ++i)
; #pragma unroll
;         for (int dt = 0; dt < 4; ++dt) o[i][dt] = (f32x4){0.f, 0.f, 0.f, 0.f};
;     Stage<DQK> st;
;     {
;         Stage<DQK> st1;
;         stage_load<DQK>(st, K0, p0, K1, p1, V, pv, 0, true, tid);
;         if (thi >= 1) stage_load<DQK>(st1, K0, p0, K1, p1, V, pv, 1, true, tid);
;         stage_store<DQK>(st, lds, true, tid);
;         if (thi >= 1) stage_store<DQK>(st1, lds + SLOT, true, tid);
;     }
;     ATT_BAR();
;     f32x4 sa[2][4], sb[2][4]; bool ca = true, cb = false;
;     x1_tile<DQK>(lds, qf, m, sa, fr, fq);
;     if (63 <= wave_tmin) x2_tile<true>(0, tpos, m, l, o, sa, fq); else x2_tile<false>(0, tpos, m, l, o, sa, fq);
.LBB0_873:
	s_or_b64 exec, exec, s[14:15]
	v_lshl_add_u64 v[44:45], s[8:9], 0, v[44:45]
	v_lshl_add_u64 v[44:45], v[44:45], 0, v[146:147]
	global_load_dwordx4 v[44:47], v[44:45], off
	v_lshrrev_b32_e32 v51, 3, v50
	v_and_b32_e32 v49, 7, v50
	v_bitop3_b32 v51, v51, v49, 15 bitop3:0x6c
	v_lshlrev_b32_e32 v155, 4, v51
	v_lshlrev_b32_e32 v153, 8, v48
	v_add_u32_e32 v51, 0, v155
	v_add_u32_e32 v51, v51, v153
	v_and_b32_e32 v78, 3, v50
	v_lshlrev_b32_e32 v157, 8, v76
	v_and_b32_e32 v79, 15, v76
	s_waitcnt vmcnt(0) lgkmcnt(0)
	ds_write_b128 v51, v[24:27]
	s_and_saveexec_b64 s[8:9], s[6:7]
	v_bitop3_b32 v52, v78, v79, 8 bitop3:0x36
	v_lshlrev_b32_e32 v52, 4, v52
	v_add3_u32 v52, 0, v52, v157
	ds_write_b128 v52, v[28:31]
	s_or_b64 exec, exec, s[8:9]
	v_lshlrev_b32_e32 v146, 4, v49
	v_mul_lo_u32 v159, v48, s76
	v_add_u32_e32 v48, 0, v146
	v_add_u32_e32 v48, v48, v159
	ds_write_b128 v48, v[32:35] offset:16384
	ds_write_b128 v51, v[36:39] offset:26624
	s_and_saveexec_b64 s[8:9], s[6:7]
	v_bitop3_b32 v36, v78, v79, 8 bitop3:0x36
	v_lshlrev_b32_e32 v36, 4, v36
	v_add3_u32 v36, 0, v36, v157
	ds_write_b128 v36, v[40:43] offset:26624
	s_or_b64 exec, exec, s[8:9]
	v_lshrrev_b32_e32 v36, 4, v50
	v_and_b32_e32 v80, 15, v50
	v_lshlrev_b32_e32 v195, 8, v80
	v_bitop3_b32 v36, v36, v80, 3 bitop3:0x6c
	ds_write_b128 v48, v[44:47] offset:43008
	v_add_u32_e32 v56, 0, v195
	v_lshlrev_b32_e32 v196, 4, v36
	s_waitcnt lgkmcnt(0)
	s_barrier
	s_xor_b64 s[58:59], s[10:11], -1
	v_lshrrev_b32_e32 v72, 6, v144
	s_lshl_b32 s8, s20, 2
	v_readfirstlane_b32 s14, v72
	s_mov_b32 s9, s8
	s_or_b32 s8, s8, 3
	s_lshr_b32 s15, s14, 1
	s_add_i32 s9, s9, s15
	s_cmp_lt_u32 s14, 4
	s_cselect_b32 s63, 1, 0
	s_mov_b32 s49, -1
	s_mov_b32 s60, 0
	s_mov_b32 s61, 0
	s_mov_b32 s62, 0xd000
	v_add_u32_e32 v155, v153, v155
	v_add_u32_e32 v159, v146, v159
	v_add_u32_e32 v159, 0x4000, v159
	v_and_b32_e32 v72, 15, v144
	v_bfe_u32 v73, v144, 4, 2
	v_lshlrev_b32_e32 v74, 8, v72
	v_xor_b32_e32 v75, v73, v72
	v_lshl_add_u32 v199, v75, 4, v74
	v_or_b32_e32 v75, 4, v73
	v_xor_b32_e32 v75, v75, v72
	v_lshl_add_u32 v201, v75, 4, v74
	v_or_b32_e32 v75, 8, v73
	v_xor_b32_e32 v75, v75, v72
	v_lshl_add_u32 v210, v75, 4, v74
	v_lshrrev_b32_e32 v75, 2, v72
	v_lshl_add_u32 v75, v73, 2, v75
	v_mul_u32_u24_e32 v75, 0xa0, v75
	v_and_b32_e32 v74, 3, v72
	v_lshl_add_u32 v251, v74, 3, v75
	v_lshlrev_b32_e32 v75, 2, v73
	v_sub_u32_e32 v151, v158, v75
	v_sub_u32_e32 v153, v156, v75
	v_lshrrev_b32_e32 v72, 2, v144
	v_and_b32_e32 v73, 3, v144
	v_or_b32_e32 v74, 8, v73
	v_and_b32_e32 v75, 15, v72
	v_xor_b32_e32 v74, v74, v75
	v_lshlrev_b32_e32 v75, 8, v72
	v_lshl_add_u32 v157, v74, 4, v75
	s_add_u32 s96, s56, s52
	s_addc_u32 s97, s57, s53
	s_add_u32 s96, s96, 0x3802000
	s_addc_u32 s97, s97, 0
	v_lshlrev_b32_e32 v72, 6, v72
	v_lshl_add_u32 v72, v73, 4, v72
	v_mov_b32_e32 v73, 0
	v_lshl_add_u64 v[166:167], s[96:97], 0, v[72:73]
	v_mov_b32_e32 v72, v146
	v_add_u32_e32 v72, 0x40000, v72
	v_lshl_add_u64 v[160:161], v[160:161], 0, v[72:73]
	v_lshl_add_u64 v[162:163], v[162:163], 0, v[72:73]
	global_load_dwordx4 v[60:63], v[160:161], off
	global_load_dwordx4 v[68:71], v[162:163], off
	s_cmp_eq_u32 s63, 0
	s_cbranch_scc1 .Lmla_nok1_0
	global_load_dwordx4 v[64:67], v[166:167], off
.Lmla_nok1_0:
	v_mov_b32_e32 v96, 0
	v_mov_b32_e32 v97, 0
	v_mov_b32_e32 v98, 0
	v_mov_b32_e32 v99, 0
	v_mov_b32_e32 v88, 0
	v_mov_b32_e32 v89, 0
	v_mov_b32_e32 v90, 0
	v_mov_b32_e32 v91, 0
	v_mov_b32_e32 v92, 0
	v_mov_b32_e32 v93, 0
	v_mov_b32_e32 v94, 0
	v_mov_b32_e32 v95, 0
	v_mov_b32_e32 v48, 0
	v_mov_b32_e32 v49, 0
	v_mov_b32_e32 v50, 0
	v_mov_b32_e32 v51, 0
	v_mov_b32_e32 v165, 0
	v_mov_b32_e32 v200, v183
	v_mov_b32_e32 v84, 0
	v_mov_b32_e32 v85, 0
	v_mov_b32_e32 v86, 0
	v_mov_b32_e32 v87, 0
	v_mov_b32_e32 v76, 0
	v_mov_b32_e32 v77, 0
	v_mov_b32_e32 v78, 0
	v_mov_b32_e32 v79, 0
	v_mov_b32_e32 v80, 0
	v_mov_b32_e32 v81, 0
	v_mov_b32_e32 v82, 0
	v_mov_b32_e32 v83, 0
	v_mov_b32_e32 v56, 0
	v_mov_b32_e32 v57, 0
	v_mov_b32_e32 v58, 0
	v_mov_b32_e32 v59, 0
	v_mov_b32_e32 v164, 0
	v_mov_b32_e32 v211, v183
	s_mov_b32 s100, 0x20000
	s_mov_b32 s101, 0
	v_cmp_lt_f32_e64 s[66:67], s77, v200
	v_cmp_lt_f32_e64 s[68:69], s77, v211
	s_nop 1
	v_cndmask_b32_e64 v197, 0, v200, s[66:67]
	v_cndmask_b32_e64 v198, 0, v211, s[68:69]
	s_and_b64 s[64:65], s[66:67], s[68:69]
	v_sub_f32_e32 v204, 0, v197
	v_mov_b32_e32 v205, v204
	v_mov_b32_e32 v206, v204
	v_mov_b32_e32 v207, v204
	v_sub_f32_e32 v252, 0, v198
	v_mov_b32_e32 v253, v252
	v_mov_b32_e32 v254, v252
	v_mov_b32_e32 v255, v252
	v_add_u32_e32 v195, s61, v199
	v_add_u32_e32 v196, s61, v201
	v_add_u32_e32 v73, s61, v210
	ds_read_b128 v[236:239], v195
	ds_read_b128 v[240:243], v196
	ds_read_b128 v[244:247], v73
	s_waitcnt lgkmcnt(0)
	v_mfma_f32_16x16x32_bf16 v[100:103], v[236:239], v[0:3], v[204:207]
	v_mfma_f32_16x16x32_bf16 v[116:119], v[236:239], v[12:15], v[252:255]
	v_mfma_f32_16x16x32_bf16 v[100:103], v[240:243], v[4:7], v[100:103]
	v_mfma_f32_16x16x32_bf16 v[116:119], v[240:243], v[16:19], v[116:119]
	v_mfma_f32_16x16x32_bf16 v[100:103], v[244:247], v[8:11], v[100:103]
	v_mfma_f32_16x16x32_bf16 v[116:119], v[244:247], v[20:23], v[116:119]
	ds_read_b128 v[236:239], v195 offset:4096
	ds_read_b128 v[240:243], v196 offset:4096
	ds_read_b128 v[244:247], v73 offset:4096
	s_waitcnt lgkmcnt(0)
	v_mfma_f32_16x16x32_bf16 v[104:107], v[236:239], v[0:3], v[204:207]
	v_mfma_f32_16x16x32_bf16 v[120:123], v[236:239], v[12:15], v[252:255]
	v_mfma_f32_16x16x32_bf16 v[104:107], v[240:243], v[4:7], v[104:107]
	v_mfma_f32_16x16x32_bf16 v[120:123], v[240:243], v[16:19], v[120:123]
	v_mfma_f32_16x16x32_bf16 v[104:107], v[244:247], v[8:11], v[104:107]
	v_mfma_f32_16x16x32_bf16 v[120:123], v[244:247], v[20:23], v[120:123]
	ds_read_b128 v[236:239], v195 offset:8192
	ds_read_b128 v[240:243], v196 offset:8192
	ds_read_b128 v[244:247], v73 offset:8192
	s_waitcnt lgkmcnt(0)
	v_mfma_f32_16x16x32_bf16 v[108:111], v[236:239], v[0:3], v[204:207]
	v_mfma_f32_16x16x32_bf16 v[124:127], v[236:239], v[12:15], v[252:255]
	v_mfma_f32_16x16x32_bf16 v[108:111], v[240:243], v[4:7], v[108:111]
	v_mfma_f32_16x16x32_bf16 v[124:127], v[240:243], v[16:19], v[124:127]
	v_mfma_f32_16x16x32_bf16 v[108:111], v[244:247], v[8:11], v[108:111]
	v_mfma_f32_16x16x32_bf16 v[124:127], v[244:247], v[20:23], v[124:127]
	ds_read_b128 v[236:239], v195 offset:12288
	ds_read_b128 v[240:243], v196 offset:12288
	ds_read_b128 v[244:247], v73 offset:12288
	s_waitcnt lgkmcnt(0)
	v_mfma_f32_16x16x32_bf16 v[112:115], v[236:239], v[0:3], v[204:207]
	v_mfma_f32_16x16x32_bf16 v[128:131], v[236:239], v[12:15], v[252:255]
	v_mfma_f32_16x16x32_bf16 v[112:115], v[240:243], v[4:7], v[112:115]
	v_mfma_f32_16x16x32_bf16 v[128:131], v[240:243], v[16:19], v[128:131]
	v_mfma_f32_16x16x32_bf16 v[112:115], v[244:247], v[8:11], v[112:115]
	v_mfma_f32_16x16x32_bf16 v[128:131], v[244:247], v[20:23], v[128:131]
	s_nop 7
	s_nop 7
	s_add_i32 s32, s49, 1
	s_cmp_eq_u32 s32, s9
	s_cbranch_scc1 .Lmla_mask1
	s_branch .Lmla_slow1_0
; #define LAS __attribute__((address_space(3)))
; __device__ __forceinline__ unsigned cvtpk(float lo, float hi) { f32x2_t v = {lo, hi}; bf16x2_t b = __builtin_convertvector(v, bf16x2_t); return __builtin_bit_cast(unsigned, b); }
; template <int I0, int NQ, int VO> __device__ __forceinline__ void tile_y(LAS unsigned char* lds, float (&l)[2], f32x4 (&o)[2][4], f32x4 (&s)[2][4], int fr, int fq) {
;     bf16x8 pb[NQ][2];
; #pragma unroll
;     for (int q = 0; q < NQ; ++q) {
;         f32x4 (&sq)[4] = s[I0 + q];
;         f32x2_t rs2 = {0.f, 0.f};
; #pragma unroll
;         for (int ss = 0; ss < 4; ++ss) {
; #pragma unroll
;             for (int i = 0; i < 4; ++i) sq[ss][i] = __builtin_amdgcn_exp2f(sq[ss][i]);
;             rs2 += (f32x2_t){sq[ss][0], sq[ss][1]}; rs2 += (f32x2_t){sq[ss][2], sq[ss][3]};
;         }
;         l[I0 + q] += rs2.x + rs2.y;
; #pragma unroll
;         for (int j = 0; j < 2; ++j) {
;             const v4u w = (v4u){cvtpk(sq[2 * j][0], sq[2 * j][1]), cvtpk(sq[2 * j][2], sq[2 * j][3]), cvtpk(sq[2 * j + 1][0], sq[2 * j + 1][1]), cvtpk(sq[2 * j + 1][2], sq[2 * j + 1][3])};
;             pb[q][j] = __builtin_bit_cast(bf16x8, w);
;         }
.Lmla_it0:
	s_add_i32 s96, s49, 2
	s_cmp_gt_u32 s96, s8
	s_cbranch_scc1 .Lmla_nostage0
	v_add_u32_e32 v72, s62, v155
	v_add_u32_e32 v73, s62, v159
	s_waitcnt vmcnt(0)
	ds_write_b128 v72, v[60:63]
	ds_write_b128 v73, v[68:71]
	s_cmp_eq_u32 s63, 0
	s_cbranch_scc1 .Lmla_nok1_10
	v_add_u32_e32 v72, s62, v157
	ds_write_b128 v72, v[64:67]
.Lmla_nok1_10:
	s_addk_i32 s62, 0x6800
	s_cmp_lt_u32 s62, 0x13800
	s_cselect_b32 s62, s62, 0
	s_cmp_ge_u32 s96, s8
	s_cbranch_scc1 .Lmla_nostage0
	v_lshl_add_u64 v[160:161], v[160:161], 0, s[100:101]
	v_lshl_add_u64 v[162:163], v[162:163], 0, s[100:101]
	s_nop 0
	global_load_dwordx4 v[60:63], v[160:161], off
	global_load_dwordx4 v[68:71], v[162:163], off
	s_cmp_eq_u32 s63, 0
	s_cbranch_scc1 .Lmla_nostage0
	v_add_co_u32_e32 v166, vcc, 0x1000, v166
	s_nop 0
	v_addc_co_u32_e32 v167, vcc, 0, v167, vcc
	s_nop 0
	global_load_dwordx4 v[64:67], v[166:167], off
.Lmla_nostage0:
	s_cmp_ge_u32 s49, s9
	s_cbranch_scc1 .Lmla_tail0
	v_add_u32_e32 v74, s60, v251
	ds_read_b64_tr_b16 v[220:221], v74 offset:16384
	ds_read_b64_tr_b16 v[222:223], v74 offset:18944
	ds_read_b64_tr_b16 v[224:225], v74 offset:21504
	ds_read_b64_tr_b16 v[226:227], v74 offset:24064
	ds_read_b64_tr_b16 v[228:229], v74 offset:16416
	ds_read_b64_tr_b16 v[230:231], v74 offset:18976
	ds_read_b64_tr_b16 v[232:233], v74 offset:21536
	ds_read_b64_tr_b16 v[234:235], v74 offset:24096
	v_add_u32_e32 v195, s61, v199
	v_add_u32_e32 v196, s61, v201
	v_add_u32_e32 v73, s61, v210
	ds_read_b128 v[236:239], v195
	ds_read_b128 v[240:243], v196
	ds_read_b128 v[244:247], v73
	s_waitcnt lgkmcnt(2)
	v_mfma_f32_16x16x32_bf16 v[24:27], v[236:239], v[0:3], v[204:207]
	v_exp_f32_e32 v100, v100
	v_mfma_f32_16x16x32_bf16 v[40:43], v[236:239], v[12:15], v[252:255]
	v_exp_f32_e32 v101, v101
	ds_read_b128 v[236:239], v195 offset:4096
	s_waitcnt lgkmcnt(2)
	v_mfma_f32_16x16x32_bf16 v[24:27], v[240:243], v[4:7], v[24:27]
	v_exp_f32_e32 v102, v102
	v_mfma_f32_16x16x32_bf16 v[40:43], v[240:243], v[16:19], v[40:43]
	v_exp_f32_e32 v103, v103
	ds_read_b128 v[240:243], v196 offset:4096
	s_waitcnt lgkmcnt(2)
	v_mfma_f32_16x16x32_bf16 v[24:27], v[244:247], v[8:11], v[24:27]
	v_exp_f32_e32 v104, v104
	v_mfma_f32_16x16x32_bf16 v[40:43], v[244:247], v[20:23], v[40:43]
	v_exp_f32_e32 v105, v105
	ds_read_b128 v[244:247], v73 offset:4096
	s_waitcnt lgkmcnt(2)
	v_mfma_f32_16x16x32_bf16 v[28:31], v[236:239], v[0:3], v[204:207]
	v_exp_f32_e32 v106, v106
	v_mfma_f32_16x16x32_bf16 v[44:47], v[236:239], v[12:15], v[252:255]
	v_exp_f32_e32 v107, v107
	ds_read_b128 v[236:239], v195 offset:8192
	s_waitcnt lgkmcnt(2)
	v_mfma_f32_16x16x32_bf16 v[28:31], v[240:243], v[4:7], v[28:31]
	v_exp_f32_e32 v108, v108
	v_mfma_f32_16x16x32_bf16 v[44:47], v[240:243], v[16:19], v[44:47]
	v_exp_f32_e32 v109, v109
	ds_read_b128 v[240:243], v196 offset:8192
	s_waitcnt lgkmcnt(2)
	v_mfma_f32_16x16x32_bf16 v[28:31], v[244:247], v[8:11], v[28:31]
	v_exp_f32_e32 v110, v110
	v_mfma_f32_16x16x32_bf16 v[44:47], v[244:247], v[20:23], v[44:47]
	v_exp_f32_e32 v111, v111
	ds_read_b128 v[244:247], v73 offset:8192
	s_waitcnt lgkmcnt(2)
	v_mfma_f32_16x16x32_bf16 v[32:35], v[236:239], v[0:3], v[204:207]
	v_exp_f32_e32 v112, v112
	v_mfma_f32_16x16x32_bf16 v[212:215], v[236:239], v[12:15], v[252:255]
	v_exp_f32_e32 v113, v113
	ds_read_b128 v[236:239], v195 offset:12288
	s_waitcnt lgkmcnt(2)
	v_mfma_f32_16x16x32_bf16 v[32:35], v[240:243], v[4:7], v[32:35]
	v_exp_f32_e32 v114, v114
	v_mfma_f32_16x16x32_bf16 v[212:215], v[240:243], v[16:19], v[212:215]
	v_exp_f32_e32 v115, v115
	ds_read_b128 v[240:243], v196 offset:12288
	s_waitcnt lgkmcnt(2)
	v_mfma_f32_16x16x32_bf16 v[32:35], v[244:247], v[8:11], v[32:35]
	v_cvt_pk_bf16_f32 v132, v100, v101
	v_cvt_pk_bf16_f32 v133, v102, v103
	v_mfma_f32_16x16x32_bf16 v[212:215], v[244:247], v[20:23], v[212:215]
	v_cvt_pk_bf16_f32 v134, v104, v105
	v_cvt_pk_bf16_f32 v135, v106, v107
	ds_read_b128 v[244:247], v73 offset:12288
	s_waitcnt lgkmcnt(2)
; template <int I0, int NQ, int VO> __device__ __forceinline__ void tile_y(LAS unsigned char* lds, float (&l)[2], f32x4 (&o)[2][4], f32x4 (&s)[2][4], int fr, int fq) {
;     bf16x8 pb[NQ][2];
; #pragma unroll
;     for (int q = 0; q < NQ; ++q) {
;         f32x4 (&sq)[4] = s[I0 + q];
;         f32x2_t rs2 = {0.f, 0.f};
; #pragma unroll
;         for (int ss = 0; ss < 4; ++ss) {
; #pragma unroll
;             for (int i = 0; i < 4; ++i) sq[ss][i] = __builtin_amdgcn_exp2f(sq[ss][i]);
;             rs2 += (f32x2_t){sq[ss][0], sq[ss][1]}; rs2 += (f32x2_t){sq[ss][2], sq[ss][3]};
;         }
;         l[I0 + q] += rs2.x + rs2.y;
; #pragma unroll
;         for (int j = 0; j < 2; ++j) {
;             const v4u w = (v4u){cvtpk(sq[2 * j][0], sq[2 * j][1]), cvtpk(sq[2 * j][2], sq[2 * j][3]), cvtpk(sq[2 * j + 1][0], sq[2 * j + 1][1]), cvtpk(sq[2 * j + 1][2], sq[2 * j + 1][3])};
;             pb[q][j] = __builtin_bit_cast(bf16x8, w);
;         }
;     }
; #pragma unroll
;     for (int dt = 0; dt < 4; ++dt)
; #pragma unroll
;         for (int j = 0; j < 2; ++j) {
;             LAS unsigned char* vp = lds + VO + ((32 * j + 4 * fq + (fr >> 2)) * VSTR + 16 * dt + 4 * (fr & 3)) * 2;
;             const s16x4 lo = __builtin_bit_cast(s16x4, __builtin_amdgcn_ds_read_tr16_b64_v4i16((LAS v4i16_t*)vp));
;             const s16x4 hi = __builtin_bit_cast(s16x4, __builtin_amdgcn_ds_read_tr16_b64_v4i16((LAS v4i16_t*)(vp + 16 * VSTR * 2)));
;             const bf16x8 vf = (bf16x8){lo[0], lo[1], lo[2], lo[3], hi[0], hi[1], hi[2], hi[3]};
; #pragma unroll
;             for (int q = 0; q < NQ; ++q) o[I0 + q][dt] = __builtin_amdgcn_mfma_f32_16x16x32_bf16(vf, pb[q][j], o[I0 + q][dt], 0, 0, 0);
;         }
; template <bool FULL> __device__ __forceinline__ void x2_tile(int kbase, const int (&tpos)[2], float (&m)[2], float (&l)[2], f32x4 (&o)[2][4], f32x4 (&s)[2][4], int fq) {
;     ...
;         if (FULL) {
;             int ia = __builtin_bit_cast(int, sq[0][0]);
;     ...
;             ia = IMX3(ia, sq[0][1], sq[0][2]); ia = IMX3(ia, sq[0][3], sq[1][0]); ia = IMX3(ia, sq[1][1], sq[1][2]); ia = IMX3(ia, sq[1][3], sq[2][0]);
;             int ib = __builtin_bit_cast(int, sq[2][1]);
;             ib = IMX3(ib, sq[2][2], sq[2][3]); ib = IMX3(ib, sq[3][0], sq[3][1]); ib = IMX3(ib, sq[3][2], sq[3][3]);
;     ...
;             const bool big = !(mo > -1e29f) || (imax2(ia, ib) > __builtin_bit_cast(int, RESCALE_THR));
	v_mfma_f32_16x16x32_bf16 v[36:39], v[236:239], v[0:3], v[204:207]
	v_cvt_pk_bf16_f32 v136, v108, v109
	v_cvt_pk_bf16_f32 v137, v110, v111
	v_mfma_f32_16x16x32_bf16 v[216:219], v[236:239], v[12:15], v[252:255]
	v_cvt_pk_bf16_f32 v138, v112, v113
	v_cvt_pk_bf16_f32 v139, v114, v115
	ds_read_b64_tr_b16 v[236:237], v74 offset:16448
	ds_read_b64_tr_b16 v[238:239], v74 offset:19008
	s_waitcnt lgkmcnt(3)
	v_mfma_f32_16x16x32_bf16 v[36:39], v[240:243], v[4:7], v[36:39]
	v_exp_f32_e32 v116, v116
	v_mfma_f32_16x16x32_bf16 v[216:219], v[240:243], v[16:19], v[216:219]
	v_exp_f32_e32 v117, v117
	ds_read_b64_tr_b16 v[240:241], v74 offset:21568
	ds_read_b64_tr_b16 v[242:243], v74 offset:24128
	s_waitcnt lgkmcnt(4)
	v_mfma_f32_16x16x32_bf16 v[36:39], v[244:247], v[8:11], v[36:39]
	v_exp_f32_e32 v118, v118
	v_mfma_f32_16x16x32_bf16 v[216:219], v[244:247], v[20:23], v[216:219]
	v_exp_f32_e32 v119, v119
	ds_read_b64_tr_b16 v[244:245], v74 offset:16480
	ds_read_b64_tr_b16 v[246:247], v74 offset:19040
	v_exp_f32_e32 v120, v120
	v_exp_f32_e32 v121, v121
	v_exp_f32_e32 v122, v122
	v_exp_f32_e32 v123, v123
	v_exp_f32_e32 v124, v124
	v_exp_f32_e32 v125, v125
	v_exp_f32_e32 v126, v126
	v_exp_f32_e32 v127, v127
	v_exp_f32_e32 v128, v128
	v_exp_f32_e32 v129, v129
	v_exp_f32_e32 v130, v130
	v_exp_f32_e32 v131, v131
	v_cvt_pk_bf16_f32 v140, v116, v117
	v_cvt_pk_bf16_f32 v141, v118, v119
	v_cvt_pk_bf16_f32 v142, v120, v121
	v_cvt_pk_bf16_f32 v143, v122, v123
	v_cvt_pk_bf16_f32 v52, v124, v125
	v_cvt_pk_bf16_f32 v53, v126, v127
	v_cvt_pk_bf16_f32 v54, v128, v129
	v_cvt_pk_bf16_f32 v55, v130, v131
	s_waitcnt lgkmcnt(15)
	v_mfma_f32_16x16x32_bf16 v[96:99], v[220:223], v[132:135], v[96:99]
	v_add_f32_e32 v100, v100, v101
	v_add_f32_e32 v102, v102, v103
	v_mfma_f32_16x16x32_bf16 v[84:87], v[220:223], v[140:143], v[84:87]
	v_add_f32_e32 v104, v104, v105
	v_add_f32_e32 v106, v106, v107
	s_waitcnt lgkmcnt(15)
	v_mfma_f32_16x16x32_bf16 v[96:99], v[224:227], v[136:139], v[96:99]
	v_add_f32_e32 v108, v108, v109
	v_add_f32_e32 v110, v110, v111
	v_mfma_f32_16x16x32_bf16 v[84:87], v[224:227], v[52:55], v[84:87]
	v_add_f32_e32 v112, v112, v113
	v_add_f32_e32 v114, v114, v115
	ds_read_b64_tr_b16 v[220:221], v74 offset:21600
	ds_read_b64_tr_b16 v[222:223], v74 offset:24160
	s_waitcnt lgkmcnt(15)
	v_mfma_f32_16x16x32_bf16 v[88:91], v[228:231], v[132:135], v[88:91]
	v_add_f32_e32 v100, v100, v102
	v_add_f32_e32 v104, v104, v106
	v_mfma_f32_16x16x32_bf16 v[76:79], v[228:231], v[140:143], v[76:79]
	v_add_f32_e32 v108, v108, v110
	v_add_f32_e32 v112, v112, v114
	s_waitcnt lgkmcnt(15)
	v_mfma_f32_16x16x32_bf16 v[88:91], v[232:235], v[136:139], v[88:91]
	v_add_f32_e32 v100, v100, v104
	v_add_f32_e32 v108, v108, v112
	v_mfma_f32_16x16x32_bf16 v[76:79], v[232:235], v[52:55], v[76:79]
	v_add_f32_e32 v100, v100, v108
	v_add_f32_e32 v165, v165, v100
	s_waitcnt lgkmcnt(6)
	v_mfma_f32_16x16x32_bf16 v[92:95], v[236:239], v[132:135], v[92:95]
	v_add_f32_e32 v116, v116, v117
	v_add_f32_e32 v118, v118, v119
	v_mfma_f32_16x16x32_bf16 v[80:83], v[236:239], v[140:143], v[80:83]
	v_add_f32_e32 v120, v120, v121
	v_add_f32_e32 v122, v122, v123
	s_waitcnt lgkmcnt(4)
	v_mfma_f32_16x16x32_bf16 v[92:95], v[240:243], v[136:139], v[92:95]
	v_add_f32_e32 v124, v124, v125
	v_add_f32_e32 v126, v126, v127
	v_mfma_f32_16x16x32_bf16 v[80:83], v[240:243], v[52:55], v[80:83]
	v_add_f32_e32 v128, v128, v129
	v_add_f32_e32 v130, v130, v131
	s_waitcnt lgkmcnt(2)
	v_mfma_f32_16x16x32_bf16 v[48:51], v[244:247], v[132:135], v[48:51]
	v_add_f32_e32 v116, v116, v118
	v_add_f32_e32 v120, v120, v122
	v_mfma_f32_16x16x32_bf16 v[56:59], v[244:247], v[140:143], v[56:59]
	v_add_f32_e32 v124, v124, v126
	v_add_f32_e32 v128, v128, v130
	s_waitcnt lgkmcnt(0)
	v_mfma_f32_16x16x32_bf16 v[48:51], v[220:223], v[136:139], v[48:51]
	v_add_f32_e32 v116, v116, v120
	v_add_f32_e32 v124, v124, v128
	v_mfma_f32_16x16x32_bf16 v[56:59], v[220:223], v[52:55], v[56:59]
	v_add_f32_e32 v116, v116, v124
	v_add_f32_e32 v164, v164, v116
	s_add_i32 s32, s49, 1
	s_cmp_eq_u32 s32, s9
	s_cbranch_scc1 .Lmla_mask0
.Lmla_chk0:
	v_max_i32_e32 v72, v24, v28
	v_max3_i32 v72, v32, v36, v72
	v_max3_i32 v72, v40, v44, v72
	v_max3_i32 v72, v212, v216, v72
	v_cmp_lt_i32_e32 vcc, s80, v72
	s_orn2_b64 vcc, vcc, s[64:65]
	s_cbranch_vccnz .Lmla_slow0_0

; #define LAS __attribute__((address_space(3)))
; template <int I0, int NQ, int VO> __device__ __forceinline__ void tile_y(LAS unsigned char* lds, float (&l)[2], f32x4 (&o)[2][4], f32x4 (&s)[2][4], int fr, int fq) {
;     bf16x8 pb[NQ][2];
; #pragma unroll
;     for (int q = 0; q < NQ; ++q) {
;         f32x4 (&sq)[4] = s[I0 + q];
;         f32x2_t rs2 = {0.f, 0.f};
; #pragma unroll
;         for (int ss = 0; ss < 4; ++ss) {
; #pragma unroll
;             for (int i = 0; i < 4; ++i) sq[ss][i] = __builtin_amdgcn_exp2f(sq[ss][i]);
;             rs2 += (f32x2_t){sq[ss][0], sq[ss][1]}; rs2 += (f32x2_t){sq[ss][2], sq[ss][3]};
;         }
;         l[I0 + q] += rs2.x + rs2.y;
; #pragma unroll
;         for (int j = 0; j < 2; ++j) {
;             const v4u w = (v4u){cvtpk(sq[2 * j][0], sq[2 * j][1]), cvtpk(sq[2 * j][2], sq[2 * j][3]), cvtpk(sq[2 * j + 1][0], sq[2 * j + 1][1]), cvtpk(sq[2 * j + 1][2], sq[2 * j + 1][3])};
;             pb[q][j] = __builtin_bit_cast(bf16x8, w);
;         }
;     }
; #pragma unroll
;     for (int dt = 0; dt < 4; ++dt)
; #pragma unroll
;         for (int j = 0; j < 2; ++j) {
;             LAS unsigned char* vp = lds + VO + ((32 * j + 4 * fq + (fr >> 2)) * VSTR + 16 * dt + 4 * (fr & 3)) * 2;
;             const s16x4 lo = __builtin_bit_cast(s16x4, __builtin_amdgcn_ds_read_tr16_b64_v4i16((LAS v4i16_t*)vp));
;             const s16x4 hi = __builtin_bit_cast(s16x4, __builtin_amdgcn_ds_read_tr16_b64_v4i16((LAS v4i16_t*)(vp + 16 * VSTR * 2)));
;             const bf16x8 vf = (bf16x8){lo[0], lo[1], lo[2], lo[3], hi[0], hi[1], hi[2], hi[3]};
; #pragma unroll
; template <int DQK> __device__ __forceinline__ void x1_tile(LAS unsigned char* lds, const bf16x8 (&qf)[2][DQK / 32], const float (&m)[2], f32x4 (&s)[2][4], int fr, int fq) {
;     constexpr int NKS = DQK / 32;
; #pragma unroll
;     for (int q = 0; q < 2; ++q) { const float c = (m[q] > -1e29f) ? -m[q] : 0.f;
; #pragma unroll
;         for (int ss = 0; ss < 4; ++ss) s[q][ss] = (f32x4){c, c, c, c}; }
; #pragma unroll
;     for (int ss = 0; ss < 4; ++ss)
; #pragma unroll
;         for (int ks = 0; ks < NKS; ++ks) {
;             const bf16x8 kf = *(const LAS bf16x8*)(lds + k_off<DQK>(16 * ss + fr, 4 * ks + fq));
; #pragma unroll
;             for (int q = 0; q < 2; ++q) s[q][ss] = __builtin_amdgcn_mfma_f32_16x16x32_bf16(kf, qf[q][ks], s[q][ss], 0, 0, 0);
;         }
; }
.Lmla_nostage1:
	s_cmp_ge_u32 s49, s9
	s_cbranch_scc1 .Lmla_tail1
	v_add_u32_e32 v74, s60, v251
	ds_read_b64_tr_b16 v[220:221], v74 offset:16384
	ds_read_b64_tr_b16 v[222:223], v74 offset:18944
	ds_read_b64_tr_b16 v[224:225], v74 offset:21504
	ds_read_b64_tr_b16 v[226:227], v74 offset:24064
	ds_read_b64_tr_b16 v[228:229], v74 offset:16416
	ds_read_b64_tr_b16 v[230:231], v74 offset:18976
	ds_read_b64_tr_b16 v[232:233], v74 offset:21536
	ds_read_b64_tr_b16 v[234:235], v74 offset:24096
	v_add_u32_e32 v195, s61, v199
	v_add_u32_e32 v196, s61, v201
	v_add_u32_e32 v73, s61, v210
	ds_read_b128 v[236:239], v195
	ds_read_b128 v[240:243], v196
	ds_read_b128 v[244:247], v73
	s_waitcnt lgkmcnt(2)
	v_mfma_f32_16x16x32_bf16 v[100:103], v[236:239], v[0:3], v[204:207]
	v_exp_f32_e32 v24, v24
	v_mfma_f32_16x16x32_bf16 v[116:119], v[236:239], v[12:15], v[252:255]
	v_exp_f32_e32 v25, v25
	ds_read_b128 v[236:239], v195 offset:4096
	s_waitcnt lgkmcnt(2)
	v_mfma_f32_16x16x32_bf16 v[100:103], v[240:243], v[4:7], v[100:103]
	v_exp_f32_e32 v26, v26
	v_mfma_f32_16x16x32_bf16 v[116:119], v[240:243], v[16:19], v[116:119]
	v_exp_f32_e32 v27, v27
	ds_read_b128 v[240:243], v196 offset:4096
	s_waitcnt lgkmcnt(2)
	v_mfma_f32_16x16x32_bf16 v[100:103], v[244:247], v[8:11], v[100:103]
	v_exp_f32_e32 v28, v28
	v_mfma_f32_16x16x32_bf16 v[116:119], v[244:247], v[20:23], v[116:119]
	v_exp_f32_e32 v29, v29
	ds_read_b128 v[244:247], v73 offset:4096
	s_waitcnt lgkmcnt(2)
	v_mfma_f32_16x16x32_bf16 v[104:107], v[236:239], v[0:3], v[204:207]
	v_exp_f32_e32 v30, v30
	v_mfma_f32_16x16x32_bf16 v[120:123], v[236:239], v[12:15], v[252:255]
	v_exp_f32_e32 v31, v31
	ds_read_b128 v[236:239], v195 offset:8192
	s_waitcnt lgkmcnt(2)
	v_mfma_f32_16x16x32_bf16 v[104:107], v[240:243], v[4:7], v[104:107]
	v_exp_f32_e32 v32, v32
	v_mfma_f32_16x16x32_bf16 v[120:123], v[240:243], v[16:19], v[120:123]
	v_exp_f32_e32 v33, v33
	ds_read_b128 v[240:243], v196 offset:8192
	s_waitcnt lgkmcnt(2)
	v_mfma_f32_16x16x32_bf16 v[104:107], v[244:247], v[8:11], v[104:107]
	v_exp_f32_e32 v34, v34
	v_mfma_f32_16x16x32_bf16 v[120:123], v[244:247], v[20:23], v[120:123]
	v_exp_f32_e32 v35, v35
	ds_read_b128 v[244:247], v73 offset:8192
	s_waitcnt lgkmcnt(2)
	v_mfma_f32_16x16x32_bf16 v[108:111], v[236:239], v[0:3], v[204:207]
	v_exp_f32_e32 v36, v36
	v_mfma_f32_16x16x32_bf16 v[124:127], v[236:239], v[12:15], v[252:255]
	v_exp_f32_e32 v37, v37
	ds_read_b128 v[236:239], v195 offset:12288
	s_waitcnt lgkmcnt(2)
	v_mfma_f32_16x16x32_bf16 v[108:111], v[240:243], v[4:7], v[108:111]
	v_exp_f32_e32 v38, v38
	v_mfma_f32_16x16x32_bf16 v[124:127], v[240:243], v[16:19], v[124:127]
	v_exp_f32_e32 v39, v39
	ds_read_b128 v[240:243], v196 offset:12288
	s_waitcnt lgkmcnt(2)
	v_mfma_f32_16x16x32_bf16 v[108:111], v[244:247], v[8:11], v[108:111]
	v_cvt_pk_bf16_f32 v132, v24, v25
	v_cvt_pk_bf16_f32 v133, v26, v27
	v_mfma_f32_16x16x32_bf16 v[124:127], v[244:247], v[20:23], v[124:127]
	v_cvt_pk_bf16_f32 v134, v28, v29
	v_cvt_pk_bf16_f32 v135, v30, v31
	ds_read_b128 v[244:247], v73 offset:12288
	s_waitcnt lgkmcnt(2)
	v_mfma_f32_16x16x32_bf16 v[112:115], v[236:239], v[0:3], v[204:207]
	v_cvt_pk_bf16_f32 v136, v32, v33
	v_cvt_pk_bf16_f32 v137, v34, v35
	v_mfma_f32_16x16x32_bf16 v[128:131], v[236:239], v[12:15], v[252:255]
	v_cvt_pk_bf16_f32 v138, v36, v37
	v_cvt_pk_bf16_f32 v139, v38, v39
	ds_read_b64_tr_b16 v[236:237], v74 offset:16448
	ds_read_b64_tr_b16 v[238:239], v74 offset:19008
	s_waitcnt lgkmcnt(3)
	v_mfma_f32_16x16x32_bf16 v[112:115], v[240:243], v[4:7], v[112:115]
	v_exp_f32_e32 v40, v40
	v_mfma_f32_16x16x32_bf16 v[128:131], v[240:243], v[16:19], v[128:131]
	v_exp_f32_e32 v41, v41
	ds_read_b64_tr_b16 v[240:241], v74 offset:21568
	ds_read_b64_tr_b16 v[242:243], v74 offset:24128
	s_waitcnt lgkmcnt(4)
	v_mfma_f32_16x16x32_bf16 v[112:115], v[244:247], v[8:11], v[112:115]
	v_exp_f32_e32 v42, v42
	v_mfma_f32_16x16x32_bf16 v[128:131], v[244:247], v[20:23], v[128:131]
	v_exp_f32_e32 v43, v43
	ds_read_b64_tr_b16 v[244:245], v74 offset:16480
	ds_read_b64_tr_b16 v[246:247], v74 offset:19040
	v_exp_f32_e32 v44, v44
	v_exp_f32_e32 v45, v45
	v_exp_f32_e32 v46, v46
	v_exp_f32_e32 v47, v47
	v_exp_f32_e32 v212, v212
	v_exp_f32_e32 v213, v213
	v_exp_f32_e32 v214, v214
	v_exp_f32_e32 v215, v215
	v_exp_f32_e32 v216, v216
	v_exp_f32_e32 v217, v217
	v_exp_f32_e32 v218, v218
	v_exp_f32_e32 v219, v219
	v_cvt_pk_bf16_f32 v140, v40, v41
	v_cvt_pk_bf16_f32 v141, v42, v43
	v_cvt_pk_bf16_f32 v142, v44, v45
	v_cvt_pk_bf16_f32 v143, v46, v47
	v_cvt_pk_bf16_f32 v52, v212, v213
	v_cvt_pk_bf16_f32 v53, v214, v215
	v_cvt_pk_bf16_f32 v54, v216, v217
	v_cvt_pk_bf16_f32 v55, v218, v219
	s_waitcnt lgkmcnt(15)
	v_mfma_f32_16x16x32_bf16 v[96:99], v[220:223], v[132:135], v[96:99]
	v_add_f32_e32 v24, v24, v25
	v_add_f32_e32 v26, v26, v27
	v_mfma_f32_16x16x32_bf16 v[84:87], v[220:223], v[140:143], v[84:87]
	v_add_f32_e32 v28, v28, v29
	v_add_f32_e32 v30, v30, v31
	s_waitcnt lgkmcnt(15)
	v_mfma_f32_16x16x32_bf16 v[96:99], v[224:227], v[136:139], v[96:99]
	v_add_f32_e32 v32, v32, v33
	v_add_f32_e32 v34, v34, v35
	v_mfma_f32_16x16x32_bf16 v[84:87], v[224:227], v[52:55], v[84:87]
	v_add_f32_e32 v36, v36, v37
	v_add_f32_e32 v38, v38, v39
	ds_read_b64_tr_b16 v[220:221], v74 offset:21600
	ds_read_b64_tr_b16 v[222:223], v74 offset:24160
	s_waitcnt lgkmcnt(15)
	v_mfma_f32_16x16x32_bf16 v[88:91], v[228:231], v[132:135], v[88:91]
	v_add_f32_e32 v24, v24, v26
	v_add_f32_e32 v28, v28, v30
	v_mfma_f32_16x16x32_bf16 v[76:79], v[228:231], v[140:143], v[76:79]
	v_add_f32_e32 v32, v32, v34
	v_add_f32_e32 v36, v36, v38
	s_waitcnt lgkmcnt(15)
	v_mfma_f32_16x16x32_bf16 v[88:91], v[232:235], v[136:139], v[88:91]
	v_add_f32_e32 v24, v24, v28
	v_add_f32_e32 v32, v32, v36
	v_mfma_f32_16x16x32_bf16 v[76:79], v[232:235], v[52:55], v[76:79]
	v_add_f32_e32 v24, v24, v32
	v_add_f32_e32 v165, v165, v24
	s_waitcnt lgkmcnt(6)
	v_mfma_f32_16x16x32_bf16 v[92:95], v[236:239], v[132:135], v[92:95]
	v_add_f32_e32 v40, v40, v41
	v_add_f32_e32 v42, v42, v43
	v_mfma_f32_16x16x32_bf16 v[80:83], v[236:239], v[140:143], v[80:83]
	v_add_f32_e32 v44, v44, v45
	v_add_f32_e32 v46, v46, v47
	s_waitcnt lgkmcnt(4)
	v_mfma_f32_16x16x32_bf16 v[92:95], v[240:243], v[136:139], v[92:95]
	v_add_f32_e32 v212, v212, v213
	v_add_f32_e32 v214, v214, v215
	v_mfma_f32_16x16x32_bf16 v[80:83], v[240:243], v[52:55], v[80:83]
	v_add_f32_e32 v216, v216, v217
	v_add_f32_e32 v218, v218, v219
	s_waitcnt lgkmcnt(2)
	v_mfma_f32_16x16x32_bf16 v[48:51], v[244:247], v[132:135], v[48:51]
	v_add_f32_e32 v40, v40, v42
	v_add_f32_e32 v44, v44, v46
	v_mfma_f32_16x16x32_bf16 v[56:59], v[244:247], v[140:143], v[56:59]
	v_add_f32_e32 v212, v212, v214
	v_add_f32_e32 v216, v216, v218
	s_waitcnt lgkmcnt(0)
	v_mfma_f32_16x16x32_bf16 v[48:51], v[220:223], v[136:139], v[48:51]
	v_add_f32_e32 v40, v40, v44
	v_add_f32_e32 v212, v212, v216
	v_mfma_f32_16x16x32_bf16 v[56:59], v[220:223], v[52:55], v[56:59]
	v_add_f32_e32 v40, v40, v212
	v_add_f32_e32 v164, v164, v40
	s_add_i32 s32, s49, 1
	s_cmp_eq_u32 s32, s9
	s_cbranch_scc1 .Lmla_mask1
; #define IMX3(a, b, c) imax2(imax2((a), __builtin_bit_cast(int, (b))), __builtin_bit_cast(int, (c)))
; #define IMX3(a, b, c) imax2(imax2((a), __builtin_bit_cast(int, (b))), __builtin_bit_cast(int, (c)))
; template <bool FULL> __device__ __forceinline__ void x2_tile(int kbase, const int (&tpos)[2], float (&m)[2], float (&l)[2], f32x4 (&o)[2][4], f32x4 (&s)[2][4], int fq) {
;     ...
;         bool slow = true;
;         if (FULL) {
;             int ia = __builtin_bit_cast(int, sq[0][0]);
;     ...
;             ia = IMX3(ia, sq[0][1], sq[0][2]); ia = IMX3(ia, sq[0][3], sq[1][0]); ia = IMX3(ia, sq[1][1], sq[1][2]); ia = IMX3(ia, sq[1][3], sq[2][0]);
;             int ib = __builtin_bit_cast(int, sq[2][1]);
;             ib = IMX3(ib, sq[2][2], sq[2][3]); ib = IMX3(ib, sq[3][0], sq[3][1]); ib = IMX3(ib, sq[3][2], sq[3][3]);
;     ...
;             const bool big = !(mo > -1e29f) || (imax2(ia, ib) > __builtin_bit_cast(int, RESCALE_THR));
;             slow = __any(big ? 1 : 0) != 0;
;         }
.Lmla_chk1:
	v_max_i32_e32 v72, v100, v104
	v_max3_i32 v72, v108, v112, v72
	v_max3_i32 v72, v116, v120, v72
	v_max3_i32 v72, v124, v128, v72
	v_cmp_lt_i32_e32 vcc, s80, v72
	s_orn2_b64 vcc, vcc, s[64:65]
	s_cbranch_vccnz .Lmla_slow1_0

; #define LAS __attribute__((address_space(3)))
; __device__ __forceinline__ unsigned cvtpk(float lo, float hi) { f32x2_t v = {lo, hi}; bf16x2_t b = __builtin_convertvector(v, bf16x2_t); return __builtin_bit_cast(unsigned, b); }
; template <int I0, int NQ, int VO> __device__ __forceinline__ void tile_y(LAS unsigned char* lds, float (&l)[2], f32x4 (&o)[2][4], f32x4 (&s)[2][4], int fr, int fq) {
;     bf16x8 pb[NQ][2];
; #pragma unroll
;     for (int q = 0; q < NQ; ++q) {
;         f32x4 (&sq)[4] = s[I0 + q];
;         f32x2_t rs2 = {0.f, 0.f};
; #pragma unroll
;         for (int ss = 0; ss < 4; ++ss) {
; #pragma unroll
;             for (int i = 0; i < 4; ++i) sq[ss][i] = __builtin_amdgcn_exp2f(sq[ss][i]);
;             rs2 += (f32x2_t){sq[ss][0], sq[ss][1]}; rs2 += (f32x2_t){sq[ss][2], sq[ss][3]};
;         }
;         l[I0 + q] += rs2.x + rs2.y;
; #pragma unroll
;         for (int j = 0; j < 2; ++j) {
;             const v4u w = (v4u){cvtpk(sq[2 * j][0], sq[2 * j][1]), cvtpk(sq[2 * j][2], sq[2 * j][3]), cvtpk(sq[2 * j + 1][0], sq[2 * j + 1][1]), cvtpk(sq[2 * j + 1][2], sq[2 * j + 1][3])};
;             pb[q][j] = __builtin_bit_cast(bf16x8, w);
;         }
;     }
; #pragma unroll
;     for (int dt = 0; dt < 4; ++dt)
; #pragma unroll
;         for (int j = 0; j < 2; ++j) {
;             LAS unsigned char* vp = lds + VO + ((32 * j + 4 * fq + (fr >> 2)) * VSTR + 16 * dt + 4 * (fr & 3)) * 2;
;             const s16x4 lo = __builtin_bit_cast(s16x4, __builtin_amdgcn_ds_read_tr16_b64_v4i16((LAS v4i16_t*)vp));
;             const s16x4 hi = __builtin_bit_cast(s16x4, __builtin_amdgcn_ds_read_tr16_b64_v4i16((LAS v4i16_t*)(vp + 16 * VSTR * 2)));
;             const bf16x8 vf = (bf16x8){lo[0], lo[1], lo[2], lo[3], hi[0], hi[1], hi[2], hi[3]};
; #pragma unroll
;             for (int q = 0; q < NQ; ++q) o[I0 + q][dt] = __builtin_amdgcn_mfma_f32_16x16x32_bf16(vf, pb[q][j], o[I0 + q][dt], 0, 0, 0);
;         }
; }
.Lmla_tail0:
	s_cmp_lg_u32 s49, s9
	s_cbranch_scc1 .Lmla_bar0
	v_add_u32_e32 v74, s60, v251
	ds_read_b64_tr_b16 v[220:221], v74 offset:16384
	ds_read_b64_tr_b16 v[222:223], v74 offset:18944
	ds_read_b64_tr_b16 v[224:225], v74 offset:21504
	ds_read_b64_tr_b16 v[226:227], v74 offset:24064
	ds_read_b64_tr_b16 v[228:229], v74 offset:16416
	ds_read_b64_tr_b16 v[230:231], v74 offset:18976
	ds_read_b64_tr_b16 v[232:233], v74 offset:21536
	ds_read_b64_tr_b16 v[234:235], v74 offset:24096
	ds_read_b64_tr_b16 v[236:237], v74 offset:16448
	ds_read_b64_tr_b16 v[238:239], v74 offset:19008
	ds_read_b64_tr_b16 v[240:241], v74 offset:21568
	ds_read_b64_tr_b16 v[242:243], v74 offset:24128
	ds_read_b64_tr_b16 v[244:245], v74 offset:16480
	ds_read_b64_tr_b16 v[246:247], v74 offset:19040
	v_exp_f32_e32 v100, v100
	v_exp_f32_e32 v101, v101
	v_exp_f32_e32 v102, v102
	v_exp_f32_e32 v103, v103
	v_exp_f32_e32 v104, v104
	v_exp_f32_e32 v105, v105
	v_exp_f32_e32 v106, v106
	v_exp_f32_e32 v107, v107
	v_exp_f32_e32 v108, v108
	v_exp_f32_e32 v109, v109
	v_exp_f32_e32 v110, v110
	v_exp_f32_e32 v111, v111
	v_exp_f32_e32 v112, v112
	v_exp_f32_e32 v113, v113
	v_exp_f32_e32 v114, v114
	v_exp_f32_e32 v115, v115
	v_cvt_pk_bf16_f32 v132, v100, v101
	v_cvt_pk_bf16_f32 v133, v102, v103
	v_cvt_pk_bf16_f32 v134, v104, v105
	v_cvt_pk_bf16_f32 v135, v106, v107
	v_cvt_pk_bf16_f32 v136, v108, v109
	v_cvt_pk_bf16_f32 v137, v110, v111
	v_cvt_pk_bf16_f32 v138, v112, v113
	v_cvt_pk_bf16_f32 v139, v114, v115
	v_add_f32_e32 v100, v100, v101
	v_add_f32_e32 v102, v102, v103
	v_add_f32_e32 v104, v104, v105
	v_add_f32_e32 v106, v106, v107
	v_add_f32_e32 v108, v108, v109
	v_add_f32_e32 v110, v110, v111
	v_add_f32_e32 v112, v112, v113
	v_add_f32_e32 v114, v114, v115
	v_add_f32_e32 v100, v100, v102
	v_add_f32_e32 v104, v104, v106
	v_add_f32_e32 v108, v108, v110
	v_add_f32_e32 v112, v112, v114
	v_add_f32_e32 v100, v100, v104
	v_add_f32_e32 v108, v108, v112
	v_add_f32_e32 v100, v100, v108
	v_add_f32_e32 v165, v165, v100
	v_exp_f32_e32 v116, v116
	v_exp_f32_e32 v117, v117
	v_exp_f32_e32 v118, v118
	v_exp_f32_e32 v119, v119
	v_exp_f32_e32 v120, v120
	v_exp_f32_e32 v121, v121
	v_exp_f32_e32 v122, v122
	v_exp_f32_e32 v123, v123
	v_exp_f32_e32 v124, v124
	v_exp_f32_e32 v125, v125
	v_exp_f32_e32 v126, v126
	v_exp_f32_e32 v127, v127
	v_exp_f32_e32 v128, v128
	v_exp_f32_e32 v129, v129
	v_exp_f32_e32 v130, v130
	v_exp_f32_e32 v131, v131
	v_cvt_pk_bf16_f32 v140, v116, v117
	v_cvt_pk_bf16_f32 v141, v118, v119
	v_cvt_pk_bf16_f32 v142, v120, v121
	v_cvt_pk_bf16_f32 v143, v122, v123
	v_cvt_pk_bf16_f32 v52, v124, v125
	v_cvt_pk_bf16_f32 v53, v126, v127
	v_cvt_pk_bf16_f32 v54, v128, v129
	v_cvt_pk_bf16_f32 v55, v130, v131
	v_add_f32_e32 v116, v116, v117
	v_add_f32_e32 v118, v118, v119
	v_add_f32_e32 v120, v120, v121
	v_add_f32_e32 v122, v122, v123
	v_add_f32_e32 v124, v124, v125
	v_add_f32_e32 v126, v126, v127
	v_add_f32_e32 v128, v128, v129
	v_add_f32_e32 v130, v130, v131
	v_add_f32_e32 v116, v116, v118
	v_add_f32_e32 v120, v120, v122
	v_add_f32_e32 v124, v124, v126
	v_add_f32_e32 v128, v128, v130
	v_add_f32_e32 v116, v116, v120
	v_add_f32_e32 v124, v124, v128
	v_add_f32_e32 v116, v116, v124
	v_add_f32_e32 v164, v164, v116
	s_waitcnt lgkmcnt(0)
	v_mfma_f32_16x16x32_bf16 v[96:99], v[220:223], v[132:135], v[96:99]
	v_mfma_f32_16x16x32_bf16 v[84:87], v[220:223], v[140:143], v[84:87]
	v_mfma_f32_16x16x32_bf16 v[96:99], v[224:227], v[136:139], v[96:99]
	v_mfma_f32_16x16x32_bf16 v[84:87], v[224:227], v[52:55], v[84:87]
	ds_read_b64_tr_b16 v[220:221], v74 offset:21600
	ds_read_b64_tr_b16 v[222:223], v74 offset:24160
	v_mfma_f32_16x16x32_bf16 v[88:91], v[228:231], v[132:135], v[88:91]
	v_mfma_f32_16x16x32_bf16 v[76:79], v[228:231], v[140:143], v[76:79]
	v_mfma_f32_16x16x32_bf16 v[88:91], v[232:235], v[136:139], v[88:91]
	v_mfma_f32_16x16x32_bf16 v[76:79], v[232:235], v[52:55], v[76:79]
	v_mfma_f32_16x16x32_bf16 v[92:95], v[236:239], v[132:135], v[92:95]
	v_mfma_f32_16x16x32_bf16 v[80:83], v[236:239], v[140:143], v[80:83]
	v_mfma_f32_16x16x32_bf16 v[92:95], v[240:243], v[136:139], v[92:95]
	v_mfma_f32_16x16x32_bf16 v[80:83], v[240:243], v[52:55], v[80:83]
	v_mfma_f32_16x16x32_bf16 v[48:51], v[244:247], v[132:135], v[48:51]
	v_mfma_f32_16x16x32_bf16 v[56:59], v[244:247], v[140:143], v[56:59]
	s_waitcnt lgkmcnt(0)
	v_mfma_f32_16x16x32_bf16 v[48:51], v[220:223], v[136:139], v[48:51]
	v_mfma_f32_16x16x32_bf16 v[56:59], v[220:223], v[52:55], v[56:59]
	s_branch .Lmla_bar0
; template <bool FULL> __device__ __forceinline__ void x2_tile(int kbase, const int (&tpos)[2], float (&m)[2], float (&l)[2], f32x4 (&o)[2][4], f32x4 (&s)[2][4], int fq) {
;     ...
;         if (slow) {
;             float mx;
;             if (FULL) {
;                 mx = fmaxf(fmaxf(sq[0][0], sq[0][1]), fmaxf(sq[0][2], sq[0][3]));
; #pragma unroll
;                 for (int ss = 1; ss < 4; ++ss) mx = fmaxf(mx, fmaxf(fmaxf(sq[ss][0], sq[ss][1]), fmaxf(sq[ss][2], sq[ss][3])));
;             } else {
;                 mx = NEG;
; #pragma unroll
;                 for (int ss = 0; ss < 4; ++ss)
; #pragma unroll
;                     for (int i = 0; i < 4; ++i) { const bool ok = (kbase + 16 * ss + 4 * fq + i) <= tpos[q]; const float v = ok ? sq[ss][i] : NEG; sq[ss][i] = v; mx = fmaxf(mx, v); }
;             }
;             mx = rows_max(mx);
;             const bool need = (mo > -1e29f) ? (mx > RESCALE_THR) : (mx > -1e29f);
;             if (__any(need ? 1 : 0)) {
;                 const float delta = need ? mx : 0.f; const float mnew = need ? meff + delta : mo; const float alpha = need ? __builtin_amdgcn_exp2f(mo - mnew) : 1.0f;
;                 l[q] *= alpha; m[q] = mnew;
; #pragma unroll
;                 for (int dt = 0; dt < 4; ++dt) o[q][dt] = o[q][dt] * alpha;
; #pragma unroll
;                 for (int ss = 0; ss < 4; ++ss) sq[ss] = sq[ss] - delta;
;             }
;         }
.Lmla_mask0:
	s_lshl_b32 s32, s32, 6
	v_subrev_u32_e32 v248, s32, v151
	v_cmp_le_i32_e64 s[90:91], 0, v248
	v_cmp_le_i32_e64 s[92:93], 1, v248
	v_cmp_le_i32_e64 s[94:95], 2, v248
	v_cndmask_b32_e64 v24, v183, v24, s[90:91]
	v_cmp_le_i32_e64 s[90:91], 3, v248
	v_cndmask_b32_e64 v25, v183, v25, s[92:93]
	v_cmp_le_i32_e64 s[92:93], 16, v248
	v_cndmask_b32_e64 v26, v183, v26, s[94:95]
	v_cmp_le_i32_e64 s[94:95], 17, v248
	v_cndmask_b32_e64 v27, v183, v27, s[90:91]
	v_cmp_le_i32_e64 s[90:91], 18, v248
	v_cndmask_b32_e64 v28, v183, v28, s[92:93]
	v_cmp_le_i32_e64 s[92:93], 19, v248
	v_cndmask_b32_e64 v29, v183, v29, s[94:95]
	v_cmp_le_i32_e64 s[94:95], 32, v248
	v_cndmask_b32_e64 v30, v183, v30, s[90:91]
	v_cmp_le_i32_e64 s[90:91], 33, v248
	v_cndmask_b32_e64 v31, v183, v31, s[92:93]
	v_cmp_le_i32_e64 s[92:93], 34, v248
	v_cndmask_b32_e64 v32, v183, v32, s[94:95]
	v_cmp_le_i32_e64 s[94:95], 35, v248
	v_cndmask_b32_e64 v33, v183, v33, s[90:91]
	v_cmp_le_i32_e64 s[90:91], 48, v248
	v_cndmask_b32_e64 v34, v183, v34, s[92:93]
	v_cmp_le_i32_e64 s[92:93], 49, v248
	v_cndmask_b32_e64 v35, v183, v35, s[94:95]
	v_cmp_le_i32_e64 s[94:95], 50, v248
	v_cndmask_b32_e64 v36, v183, v36, s[90:91]
	v_cmp_le_i32_e64 s[90:91], 51, v248
	s_nop 1
	v_cndmask_b32_e64 v37, v183, v37, s[92:93]
	v_cndmask_b32_e64 v38, v183, v38, s[94:95]
	v_cndmask_b32_e64 v39, v183, v39, s[90:91]
	v_subrev_u32_e32 v249, s32, v153
	v_cmp_le_i32_e64 s[90:91], 0, v249
	v_cmp_le_i32_e64 s[92:93], 1, v249
	v_cmp_le_i32_e64 s[94:95], 2, v249
	v_cndmask_b32_e64 v40, v183, v40, s[90:91]
	v_cmp_le_i32_e64 s[90:91], 3, v249
	v_cndmask_b32_e64 v41, v183, v41, s[92:93]
	v_cmp_le_i32_e64 s[92:93], 16, v249
	v_cndmask_b32_e64 v42, v183, v42, s[94:95]
	v_cmp_le_i32_e64 s[94:95], 17, v249
	v_cndmask_b32_e64 v43, v183, v43, s[90:91]
	v_cmp_le_i32_e64 s[90:91], 18, v249
	v_cndmask_b32_e64 v44, v183, v44, s[92:93]
	v_cmp_le_i32_e64 s[92:93], 19, v249
	v_cndmask_b32_e64 v45, v183, v45, s[94:95]
	v_cmp_le_i32_e64 s[94:95], 32, v249
	v_cndmask_b32_e64 v46, v183, v46, s[90:91]
	v_cmp_le_i32_e64 s[90:91], 33, v249
	v_cndmask_b32_e64 v47, v183, v47, s[92:93]
	v_cmp_le_i32_e64 s[92:93], 34, v249
	v_cndmask_b32_e64 v212, v183, v212, s[94:95]
	v_cmp_le_i32_e64 s[94:95], 35, v249
	v_cndmask_b32_e64 v213, v183, v213, s[90:91]
	v_cmp_le_i32_e64 s[90:91], 48, v249
	v_cndmask_b32_e64 v214, v183, v214, s[92:93]
	v_cmp_le_i32_e64 s[92:93], 49, v249
	v_cndmask_b32_e64 v215, v183, v215, s[94:95]
	v_cmp_le_i32_e64 s[94:95], 50, v249
	v_cndmask_b32_e64 v216, v183, v216, s[90:91]
	v_cmp_le_i32_e64 s[90:91], 51, v249
	s_nop 1
	v_cndmask_b32_e64 v217, v183, v217, s[92:93]
	v_cndmask_b32_e64 v218, v183, v218, s[94:95]
	v_cndmask_b32_e64 v219, v183, v219, s[90:91]
.Lmla_slow0_0:
	s_nop 7
	s_nop 7
	v_max3_f32 v72, v24, v25, v26
	v_max3_f32 v72, v72, v27, v28
	v_max3_f32 v72, v72, v29, v30
	v_max3_f32 v72, v72, v31, v32
	v_max3_f32 v72, v72, v33, v34
	v_max3_f32 v72, v72, v35, v36
	v_max3_f32 v72, v72, v37, v38
	v_max_f32_e32 v72, v72, v39
	v_mov_b32_e32 v73, v72
	s_nop 1
	v_permlane16_swap_b32_e32 v72, v73
	v_max_f32_e32 v72, v72, v73
	v_mov_b32_e32 v73, v72
	s_nop 1
	v_permlane32_swap_b32_e32 v72, v73
	v_max_f32_e32 v74, v72, v73
	v_cmp_lt_f32_e64 s[70:71], s80, v74
	v_cmp_lt_f32_e64 s[72:73], s77, v74
	s_and_b64 s[70:71], s[70:71], s[66:67]
	s_andn2_b64 s[72:73], s[72:73], s[66:67]
	s_or_b64 s[70:71], s[70:71], s[72:73]
	s_cmp_lg_u64 s[70:71], 0
	s_cbranch_scc0 .Lmla_slow0_1
	v_add_f32_e32 v72, v197, v74
	v_cndmask_b32_e64 v75, 0, v74, s[70:71]
	v_cndmask_b32_e64 v208, v200, v72, s[70:71]
	v_sub_f32_e32 v72, v200, v208
	v_exp_f32_e32 v72, v72
	v_mov_b32_e32 v200, v208
	v_cndmask_b32_e64 v209, 1.0, v72, s[70:71]
	v_mul_f32_e32 v165, v165, v209
	v_mul_f32_e32 v96, v96, v209
	v_mul_f32_e32 v97, v97, v209
	v_mul_f32_e32 v98, v98, v209
	v_mul_f32_e32 v99, v99, v209
	v_mul_f32_e32 v88, v88, v209
	v_mul_f32_e32 v89, v89, v209
	v_mul_f32_e32 v90, v90, v209
	v_mul_f32_e32 v91, v91, v209
	v_mul_f32_e32 v92, v92, v209
	v_mul_f32_e32 v93, v93, v209
	v_mul_f32_e32 v94, v94, v209
	v_mul_f32_e32 v95, v95, v209
	v_mul_f32_e32 v48, v48, v209
	v_mul_f32_e32 v49, v49, v209
	v_mul_f32_e32 v50, v50, v209
	v_mul_f32_e32 v51, v51, v209
	v_sub_f32_e32 v24, v24, v75
	v_sub_f32_e32 v25, v25, v75
	v_sub_f32_e32 v26, v26, v75
	v_sub_f32_e32 v27, v27, v75
	v_sub_f32_e32 v28, v28, v75
	v_sub_f32_e32 v29, v29, v75
	v_sub_f32_e32 v30, v30, v75
	v_sub_f32_e32 v31, v31, v75
	v_sub_f32_e32 v32, v32, v75
	v_sub_f32_e32 v33, v33, v75
	v_sub_f32_e32 v34, v34, v75
	v_sub_f32_e32 v35, v35, v75
	v_sub_f32_e32 v36, v36, v75
	v_sub_f32_e32 v37, v37, v75
	v_sub_f32_e32 v38, v38, v75
	v_sub_f32_e32 v39, v39, v75
	v_cmp_lt_f32_e64 s[66:67], s77, v200
	s_nop 1
	v_cndmask_b32_e64 v197, 0, v200, s[66:67]
	s_and_b64 s[64:65], s[66:67], s[68:69]
	v_sub_f32_e32 v204, 0, v197
	v_mov_b32_e32 v205, v204
	v_mov_b32_e32 v206, v204
	v_mov_b32_e32 v207, v204
; template <int I0, int NQ, int VO> __device__ __forceinline__ void tile_y(LAS unsigned char* lds, float (&l)[2], f32x4 (&o)[2][4], f32x4 (&s)[2][4], int fr, int fq) {
;     bf16x8 pb[NQ][2];
; #pragma unroll
;     for (int q = 0; q < NQ; ++q) {
;         f32x4 (&sq)[4] = s[I0 + q];
;         f32x2_t rs2 = {0.f, 0.f};
; #pragma unroll
;         for (int ss = 0; ss < 4; ++ss) {
; #pragma unroll
;             for (int i = 0; i < 4; ++i) sq[ss][i] = __builtin_amdgcn_exp2f(sq[ss][i]);
;             rs2 += (f32x2_t){sq[ss][0], sq[ss][1]}; rs2 += (f32x2_t){sq[ss][2], sq[ss][3]};
;         }
;         l[I0 + q] += rs2.x + rs2.y;
; #pragma unroll
;         for (int j = 0; j < 2; ++j) {
;             const v4u w = (v4u){cvtpk(sq[2 * j][0], sq[2 * j][1]), cvtpk(sq[2 * j][2], sq[2 * j][3]), cvtpk(sq[2 * j + 1][0], sq[2 * j + 1][1]), cvtpk(sq[2 * j + 1][2], sq[2 * j + 1][3])};
;             pb[q][j] = __builtin_bit_cast(bf16x8, w);
;         }
;     }
; #pragma unroll
; template <bool FULL> __device__ __forceinline__ void x2_tile(int kbase, const int (&tpos)[2], float (&m)[2], float (&l)[2], f32x4 (&o)[2][4], f32x4 (&s)[2][4], int fq) {
;     ...
;         if (slow) {
;             float mx;
;             if (FULL) {
;                 mx = fmaxf(fmaxf(sq[0][0], sq[0][1]), fmaxf(sq[0][2], sq[0][3]));
; #pragma unroll
;                 for (int ss = 1; ss < 4; ++ss) mx = fmaxf(mx, fmaxf(fmaxf(sq[ss][0], sq[ss][1]), fmaxf(sq[ss][2], sq[ss][3])));
;             } else {
;                 mx = NEG;
; #pragma unroll
;                 for (int ss = 0; ss < 4; ++ss)
; #pragma unroll
;                     for (int i = 0; i < 4; ++i) { const bool ok = (kbase + 16 * ss + 4 * fq + i) <= tpos[q]; const float v = ok ? sq[ss][i] : NEG; sq[ss][i] = v; mx = fmaxf(mx, v); }
;             }
;             mx = rows_max(mx);
;             const bool need = (mo > -1e29f) ? (mx > RESCALE_THR) : (mx > -1e29f);
;             if (__any(need ? 1 : 0)) {
;                 const float delta = need ? mx : 0.f; const float mnew = need ? meff + delta : mo; const float alpha = need ? __builtin_amdgcn_exp2f(mo - mnew) : 1.0f;
;                 l[q] *= alpha; m[q] = mnew;
; #pragma unroll
;                 for (int dt = 0; dt < 4; ++dt) o[q][dt] = o[q][dt] * alpha;
; #pragma unroll
;                 for (int ss = 0; ss < 4; ++ss) sq[ss] = sq[ss] - delta;
;             }
;         }
.Lmla_slow0_1:
	s_nop 7
	s_nop 7
	v_max3_f32 v72, v40, v41, v42
	v_max3_f32 v72, v72, v43, v44
	v_max3_f32 v72, v72, v45, v46
	v_max3_f32 v72, v72, v47, v212
	v_max3_f32 v72, v72, v213, v214
	v_max3_f32 v72, v72, v215, v216
	v_max3_f32 v72, v72, v217, v218
	v_max_f32_e32 v72, v72, v219
	v_mov_b32_e32 v73, v72
	s_nop 1
	v_permlane16_swap_b32_e32 v72, v73
	v_max_f32_e32 v72, v72, v73
	v_mov_b32_e32 v73, v72
	s_nop 1
	v_permlane32_swap_b32_e32 v72, v73
	v_max_f32_e32 v74, v72, v73
	v_cmp_lt_f32_e64 s[70:71], s80, v74
	v_cmp_lt_f32_e64 s[72:73], s77, v74
	s_and_b64 s[70:71], s[70:71], s[68:69]
	s_andn2_b64 s[72:73], s[72:73], s[68:69]
	s_or_b64 s[70:71], s[70:71], s[72:73]
	s_cmp_lg_u64 s[70:71], 0
	s_cbranch_scc0 .Lmla_bar0
	v_add_f32_e32 v72, v198, v74
	v_cndmask_b32_e64 v75, 0, v74, s[70:71]
	v_cndmask_b32_e64 v208, v211, v72, s[70:71]
	v_sub_f32_e32 v72, v211, v208
	v_exp_f32_e32 v72, v72
	v_mov_b32_e32 v211, v208
	v_cndmask_b32_e64 v209, 1.0, v72, s[70:71]
	v_mul_f32_e32 v164, v164, v209
	v_mul_f32_e32 v84, v84, v209
	v_mul_f32_e32 v85, v85, v209
	v_mul_f32_e32 v86, v86, v209
	v_mul_f32_e32 v87, v87, v209
	v_mul_f32_e32 v76, v76, v209
	v_mul_f32_e32 v77, v77, v209
	v_mul_f32_e32 v78, v78, v209
	v_mul_f32_e32 v79, v79, v209
	v_mul_f32_e32 v80, v80, v209
	v_mul_f32_e32 v81, v81, v209
	v_mul_f32_e32 v82, v82, v209
	v_mul_f32_e32 v83, v83, v209
	v_mul_f32_e32 v56, v56, v209
	v_mul_f32_e32 v57, v57, v209
	v_mul_f32_e32 v58, v58, v209
	v_mul_f32_e32 v59, v59, v209
	v_sub_f32_e32 v40, v40, v75
	v_sub_f32_e32 v41, v41, v75
	v_sub_f32_e32 v42, v42, v75
	v_sub_f32_e32 v43, v43, v75
	v_sub_f32_e32 v44, v44, v75
	v_sub_f32_e32 v45, v45, v75
	v_sub_f32_e32 v46, v46, v75
	v_sub_f32_e32 v47, v47, v75
	v_sub_f32_e32 v212, v212, v75
	v_sub_f32_e32 v213, v213, v75
	v_sub_f32_e32 v214, v214, v75
	v_sub_f32_e32 v215, v215, v75
	v_sub_f32_e32 v216, v216, v75
	v_sub_f32_e32 v217, v217, v75
	v_sub_f32_e32 v218, v218, v75
	v_sub_f32_e32 v219, v219, v75
	v_cmp_lt_f32_e64 s[68:69], s77, v211
	s_nop 1
	v_cndmask_b32_e64 v198, 0, v211, s[68:69]
	s_and_b64 s[64:65], s[66:67], s[68:69]
	v_sub_f32_e32 v252, 0, v198
	v_mov_b32_e32 v253, v252
	v_mov_b32_e32 v254, v252
	v_mov_b32_e32 v255, v252
	s_branch .Lmla_bar0
.Lmla_tail1:
	s_cmp_lg_u32 s49, s9
	s_cbranch_scc1 .Lmla_bar1
	v_add_u32_e32 v74, s60, v251
	ds_read_b64_tr_b16 v[220:221], v74 offset:16384
	ds_read_b64_tr_b16 v[222:223], v74 offset:18944
	ds_read_b64_tr_b16 v[224:225], v74 offset:21504
	ds_read_b64_tr_b16 v[226:227], v74 offset:24064
	ds_read_b64_tr_b16 v[228:229], v74 offset:16416
	ds_read_b64_tr_b16 v[230:231], v74 offset:18976
	ds_read_b64_tr_b16 v[232:233], v74 offset:21536
	ds_read_b64_tr_b16 v[234:235], v74 offset:24096
	ds_read_b64_tr_b16 v[236:237], v74 offset:16448
	ds_read_b64_tr_b16 v[238:239], v74 offset:19008
	ds_read_b64_tr_b16 v[240:241], v74 offset:21568
	ds_read_b64_tr_b16 v[242:243], v74 offset:24128
	ds_read_b64_tr_b16 v[244:245], v74 offset:16480
	ds_read_b64_tr_b16 v[246:247], v74 offset:19040
	v_exp_f32_e32 v24, v24
	v_exp_f32_e32 v25, v25
	v_exp_f32_e32 v26, v26
	v_exp_f32_e32 v27, v27
	v_exp_f32_e32 v28, v28
	v_exp_f32_e32 v29, v29
	v_exp_f32_e32 v30, v30
	v_exp_f32_e32 v31, v31
	v_exp_f32_e32 v32, v32
	v_exp_f32_e32 v33, v33
	v_exp_f32_e32 v34, v34
	v_exp_f32_e32 v35, v35
	v_exp_f32_e32 v36, v36
	v_exp_f32_e32 v37, v37
	v_exp_f32_e32 v38, v38
	v_exp_f32_e32 v39, v39
	v_cvt_pk_bf16_f32 v132, v24, v25
	v_cvt_pk_bf16_f32 v133, v26, v27
	v_cvt_pk_bf16_f32 v134, v28, v29
	v_cvt_pk_bf16_f32 v135, v30, v31
	v_cvt_pk_bf16_f32 v136, v32, v33
	v_cvt_pk_bf16_f32 v137, v34, v35
	v_cvt_pk_bf16_f32 v138, v36, v37
	v_cvt_pk_bf16_f32 v139, v38, v39
	v_add_f32_e32 v24, v24, v25
	v_add_f32_e32 v26, v26, v27
	v_add_f32_e32 v28, v28, v29
	v_add_f32_e32 v30, v30, v31
	v_add_f32_e32 v32, v32, v33
	v_add_f32_e32 v34, v34, v35
	v_add_f32_e32 v36, v36, v37
	v_add_f32_e32 v38, v38, v39
	v_add_f32_e32 v24, v24, v26
	v_add_f32_e32 v28, v28, v30
	v_add_f32_e32 v32, v32, v34
	v_add_f32_e32 v36, v36, v38
	v_add_f32_e32 v24, v24, v28
	v_add_f32_e32 v32, v32, v36
	v_add_f32_e32 v24, v24, v32
	v_add_f32_e32 v165, v165, v24
	v_exp_f32_e32 v40, v40
	v_exp_f32_e32 v41, v41
	v_exp_f32_e32 v42, v42
	v_exp_f32_e32 v43, v43
	v_exp_f32_e32 v44, v44
	v_exp_f32_e32 v45, v45
	v_exp_f32_e32 v46, v46
	v_exp_f32_e32 v47, v47
	v_exp_f32_e32 v212, v212
	v_exp_f32_e32 v213, v213
	v_exp_f32_e32 v214, v214
	v_exp_f32_e32 v215, v215
	v_exp_f32_e32 v216, v216
	v_exp_f32_e32 v217, v217
	v_exp_f32_e32 v218, v218
	v_exp_f32_e32 v219, v219
	v_cvt_pk_bf16_f32 v140, v40, v41
	v_cvt_pk_bf16_f32 v141, v42, v43
	v_cvt_pk_bf16_f32 v142, v44, v45
	v_cvt_pk_bf16_f32 v143, v46, v47
	v_cvt_pk_bf16_f32 v52, v212, v213
	v_cvt_pk_bf16_f32 v53, v214, v215
	v_cvt_pk_bf16_f32 v54, v216, v217
	v_cvt_pk_bf16_f32 v55, v218, v219
	v_add_f32_e32 v40, v40, v41
	v_add_f32_e32 v42, v42, v43
	v_add_f32_e32 v44, v44, v45
	v_add_f32_e32 v46, v46, v47
	v_add_f32_e32 v212, v212, v213
	v_add_f32_e32 v214, v214, v215
	v_add_f32_e32 v216, v216, v217
	v_add_f32_e32 v218, v218, v219
	v_add_f32_e32 v40, v40, v42
	v_add_f32_e32 v44, v44, v46
	v_add_f32_e32 v212, v212, v214
	v_add_f32_e32 v216, v216, v218
	v_add_f32_e32 v40, v40, v44
	v_add_f32_e32 v212, v212, v216
	v_add_f32_e32 v40, v40, v212
	v_add_f32_e32 v164, v164, v40
	s_waitcnt lgkmcnt(0)
	v_mfma_f32_16x16x32_bf16 v[96:99], v[220:223], v[132:135], v[96:99]
	v_mfma_f32_16x16x32_bf16 v[84:87], v[220:223], v[140:143], v[84:87]
	v_mfma_f32_16x16x32_bf16 v[96:99], v[224:227], v[136:139], v[96:99]
	v_mfma_f32_16x16x32_bf16 v[84:87], v[224:227], v[52:55], v[84:87]
	ds_read_b64_tr_b16 v[220:221], v74 offset:21600
	ds_read_b64_tr_b16 v[222:223], v74 offset:24160
	v_mfma_f32_16x16x32_bf16 v[88:91], v[228:231], v[132:135], v[88:91]
	v_mfma_f32_16x16x32_bf16 v[76:79], v[228:231], v[140:143], v[76:79]
	v_mfma_f32_16x16x32_bf16 v[88:91], v[232:235], v[136:139], v[88:91]
	v_mfma_f32_16x16x32_bf16 v[76:79], v[232:235], v[52:55], v[76:79]
	v_mfma_f32_16x16x32_bf16 v[92:95], v[236:239], v[132:135], v[92:95]
	v_mfma_f32_16x16x32_bf16 v[80:83], v[236:239], v[140:143], v[80:83]
	v_mfma_f32_16x16x32_bf16 v[92:95], v[240:243], v[136:139], v[92:95]
	v_mfma_f32_16x16x32_bf16 v[80:83], v[240:243], v[52:55], v[80:83]
	v_mfma_f32_16x16x32_bf16 v[48:51], v[244:247], v[132:135], v[48:51]
	v_mfma_f32_16x16x32_bf16 v[56:59], v[244:247], v[140:143], v[56:59]
	s_waitcnt lgkmcnt(0)
	v_mfma_f32_16x16x32_bf16 v[48:51], v[220:223], v[136:139], v[48:51]
	v_mfma_f32_16x16x32_bf16 v[56:59], v[220:223], v[52:55], v[56:59]
	s_branch .Lmla_bar1
; template <bool FULL> __device__ __forceinline__ void x2_tile(int kbase, const int (&tpos)[2], float (&m)[2], float (&l)[2], f32x4 (&o)[2][4], f32x4 (&s)[2][4], int fq) {
;     ...
;             } else {
;                 mx = NEG;
; #pragma unroll
;                 for (int ss = 0; ss < 4; ++ss)
; #pragma unroll
;                     for (int i = 0; i < 4; ++i) { const bool ok = (kbase + 16 * ss + 4 * fq + i) <= tpos[q]; const float v = ok ? sq[ss][i] : NEG; sq[ss][i] = v; mx = fmaxf(mx, v); }
;             }
.Lmla_mask1:
	s_lshl_b32 s32, s32, 6
	v_subrev_u32_e32 v248, s32, v151
	v_cmp_le_i32_e64 s[90:91], 0, v248
	v_cmp_le_i32_e64 s[92:93], 1, v248
	v_cmp_le_i32_e64 s[94:95], 2, v248
	v_cndmask_b32_e64 v100, v183, v100, s[90:91]
	v_cmp_le_i32_e64 s[90:91], 3, v248
	v_cndmask_b32_e64 v101, v183, v101, s[92:93]
	v_cmp_le_i32_e64 s[92:93], 16, v248
	v_cndmask_b32_e64 v102, v183, v102, s[94:95]
	v_cmp_le_i32_e64 s[94:95], 17, v248
	v_cndmask_b32_e64 v103, v183, v103, s[90:91]
	v_cmp_le_i32_e64 s[90:91], 18, v248
	v_cndmask_b32_e64 v104, v183, v104, s[92:93]
	v_cmp_le_i32_e64 s[92:93], 19, v248
	v_cndmask_b32_e64 v105, v183, v105, s[94:95]
	v_cmp_le_i32_e64 s[94:95], 32, v248
	v_cndmask_b32_e64 v106, v183, v106, s[90:91]
	v_cmp_le_i32_e64 s[90:91], 33, v248
	v_cndmask_b32_e64 v107, v183, v107, s[92:93]
	v_cmp_le_i32_e64 s[92:93], 34, v248
	v_cndmask_b32_e64 v108, v183, v108, s[94:95]
	v_cmp_le_i32_e64 s[94:95], 35, v248
	v_cndmask_b32_e64 v109, v183, v109, s[90:91]
	v_cmp_le_i32_e64 s[90:91], 48, v248
	v_cndmask_b32_e64 v110, v183, v110, s[92:93]
	v_cmp_le_i32_e64 s[92:93], 49, v248
	v_cndmask_b32_e64 v111, v183, v111, s[94:95]
	v_cmp_le_i32_e64 s[94:95], 50, v248
	v_cndmask_b32_e64 v112, v183, v112, s[90:91]
	v_cmp_le_i32_e64 s[90:91], 51, v248
	s_nop 1
	v_cndmask_b32_e64 v113, v183, v113, s[92:93]
	v_cndmask_b32_e64 v114, v183, v114, s[94:95]
	v_cndmask_b32_e64 v115, v183, v115, s[90:91]
	v_subrev_u32_e32 v249, s32, v153
	v_cmp_le_i32_e64 s[90:91], 0, v249
	v_cmp_le_i32_e64 s[92:93], 1, v249
	v_cmp_le_i32_e64 s[94:95], 2, v249
	v_cndmask_b32_e64 v116, v183, v116, s[90:91]
	v_cmp_le_i32_e64 s[90:91], 3, v249
	v_cndmask_b32_e64 v117, v183, v117, s[92:93]
	v_cmp_le_i32_e64 s[92:93], 16, v249
	v_cndmask_b32_e64 v118, v183, v118, s[94:95]
	v_cmp_le_i32_e64 s[94:95], 17, v249
	v_cndmask_b32_e64 v119, v183, v119, s[90:91]
	v_cmp_le_i32_e64 s[90:91], 18, v249
	v_cndmask_b32_e64 v120, v183, v120, s[92:93]
	v_cmp_le_i32_e64 s[92:93], 19, v249
	v_cndmask_b32_e64 v121, v183, v121, s[94:95]
	v_cmp_le_i32_e64 s[94:95], 32, v249
	v_cndmask_b32_e64 v122, v183, v122, s[90:91]
	v_cmp_le_i32_e64 s[90:91], 33, v249
	v_cndmask_b32_e64 v123, v183, v123, s[92:93]
	v_cmp_le_i32_e64 s[92:93], 34, v249
	v_cndmask_b32_e64 v124, v183, v124, s[94:95]
	v_cmp_le_i32_e64 s[94:95], 35, v249
	v_cndmask_b32_e64 v125, v183, v125, s[90:91]
	v_cmp_le_i32_e64 s[90:91], 48, v249
	v_cndmask_b32_e64 v126, v183, v126, s[92:93]
	v_cmp_le_i32_e64 s[92:93], 49, v249
	v_cndmask_b32_e64 v127, v183, v127, s[94:95]
	v_cmp_le_i32_e64 s[94:95], 50, v249
	v_cndmask_b32_e64 v128, v183, v128, s[90:91]
	v_cmp_le_i32_e64 s[90:91], 51, v249
	s_nop 1
	v_cndmask_b32_e64 v129, v183, v129, s[92:93]
	v_cndmask_b32_e64 v130, v183, v130, s[94:95]
	v_cndmask_b32_e64 v131, v183, v131, s[90:91]
; template <bool FULL> __device__ __forceinline__ void x2_tile(int kbase, const int (&tpos)[2], float (&m)[2], float (&l)[2], f32x4 (&o)[2][4], f32x4 (&s)[2][4], int fq) {
;     ...
;         if (slow) {
;             float mx;
;             if (FULL) {
;                 mx = fmaxf(fmaxf(sq[0][0], sq[0][1]), fmaxf(sq[0][2], sq[0][3]));
; #pragma unroll
;                 for (int ss = 1; ss < 4; ++ss) mx = fmaxf(mx, fmaxf(fmaxf(sq[ss][0], sq[ss][1]), fmaxf(sq[ss][2], sq[ss][3])));
;             } else {
;                 mx = NEG;
; #pragma unroll
;                 for (int ss = 0; ss < 4; ++ss)
; #pragma unroll
;                     for (int i = 0; i < 4; ++i) { const bool ok = (kbase + 16 * ss + 4 * fq + i) <= tpos[q]; const float v = ok ? sq[ss][i] : NEG; sq[ss][i] = v; mx = fmaxf(mx, v); }
;             }
;             mx = rows_max(mx);
;             const bool need = (mo > -1e29f) ? (mx > RESCALE_THR) : (mx > -1e29f);
;             if (__any(need ? 1 : 0)) {
;                 const float delta = need ? mx : 0.f; const float mnew = need ? meff + delta : mo; const float alpha = need ? __builtin_amdgcn_exp2f(mo - mnew) : 1.0f;
;                 l[q] *= alpha; m[q] = mnew;
; #pragma unroll
;                 for (int dt = 0; dt < 4; ++dt) o[q][dt] = o[q][dt] * alpha;
; #pragma unroll
;                 for (int ss = 0; ss < 4; ++ss) sq[ss] = sq[ss] - delta;
;             }
;         }
.Lmla_slow1_0:
	s_nop 7
	s_nop 7
	v_max3_f32 v72, v100, v101, v102
	v_max3_f32 v72, v72, v103, v104
	v_max3_f32 v72, v72, v105, v106
	v_max3_f32 v72, v72, v107, v108
	v_max3_f32 v72, v72, v109, v110
	v_max3_f32 v72, v72, v111, v112
	v_max3_f32 v72, v72, v113, v114
	v_max_f32_e32 v72, v72, v115
	v_mov_b32_e32 v73, v72
	s_nop 1
	v_permlane16_swap_b32_e32 v72, v73
	v_max_f32_e32 v72, v72, v73
	v_mov_b32_e32 v73, v72
	s_nop 1
	v_permlane32_swap_b32_e32 v72, v73
	v_max_f32_e32 v74, v72, v73
	v_cmp_lt_f32_e64 s[70:71], s80, v74
	v_cmp_lt_f32_e64 s[72:73], s77, v74
	s_and_b64 s[70:71], s[70:71], s[66:67]
	s_andn2_b64 s[72:73], s[72:73], s[66:67]
	s_or_b64 s[70:71], s[70:71], s[72:73]
	s_cmp_lg_u64 s[70:71], 0
	s_cbranch_scc0 .Lmla_slow1_1
	v_add_f32_e32 v72, v197, v74
	v_cndmask_b32_e64 v75, 0, v74, s[70:71]
	v_cndmask_b32_e64 v208, v200, v72, s[70:71]
	v_sub_f32_e32 v72, v200, v208
	v_exp_f32_e32 v72, v72
	v_mov_b32_e32 v200, v208
	v_cndmask_b32_e64 v209, 1.0, v72, s[70:71]
	v_mul_f32_e32 v165, v165, v209
	v_mul_f32_e32 v96, v96, v209
	v_mul_f32_e32 v97, v97, v209
	v_mul_f32_e32 v98, v98, v209
	v_mul_f32_e32 v99, v99, v209
	v_mul_f32_e32 v88, v88, v209
	v_mul_f32_e32 v89, v89, v209
	v_mul_f32_e32 v90, v90, v209
	v_mul_f32_e32 v91, v91, v209
	v_mul_f32_e32 v92, v92, v209
	v_mul_f32_e32 v93, v93, v209
	v_mul_f32_e32 v94, v94, v209
	v_mul_f32_e32 v95, v95, v209
	v_mul_f32_e32 v48, v48, v209
	v_mul_f32_e32 v49, v49, v209
	v_mul_f32_e32 v50, v50, v209
	v_mul_f32_e32 v51, v51, v209
	v_sub_f32_e32 v100, v100, v75
	v_sub_f32_e32 v101, v101, v75
	v_sub_f32_e32 v102, v102, v75
	v_sub_f32_e32 v103, v103, v75
	v_sub_f32_e32 v104, v104, v75
	v_sub_f32_e32 v105, v105, v75
	v_sub_f32_e32 v106, v106, v75
	v_sub_f32_e32 v107, v107, v75
	v_sub_f32_e32 v108, v108, v75
	v_sub_f32_e32 v109, v109, v75
	v_sub_f32_e32 v110, v110, v75
	v_sub_f32_e32 v111, v111, v75
	v_sub_f32_e32 v112, v112, v75
	v_sub_f32_e32 v113, v113, v75
	v_sub_f32_e32 v114, v114, v75
	v_sub_f32_e32 v115, v115, v75
	v_cmp_lt_f32_e64 s[66:67], s77, v200
	s_nop 1
	v_cndmask_b32_e64 v197, 0, v200, s[66:67]
	s_and_b64 s[64:65], s[66:67], s[68:69]
	v_sub_f32_e32 v204, 0, v197
	v_mov_b32_e32 v205, v204
	v_mov_b32_e32 v206, v204
	v_mov_b32_e32 v207, v204
.Lmla_slow1_1:
	s_nop 7
	s_nop 7
	v_max3_f32 v72, v116, v117, v118
	v_max3_f32 v72, v72, v119, v120
	v_max3_f32 v72, v72, v121, v122
	v_max3_f32 v72, v72, v123, v124
	v_max3_f32 v72, v72, v125, v126
	v_max3_f32 v72, v72, v127, v128
	v_max3_f32 v72, v72, v129, v130
	v_max_f32_e32 v72, v72, v131
	v_mov_b32_e32 v73, v72
	s_nop 1
	v_permlane16_swap_b32_e32 v72, v73
	v_max_f32_e32 v72, v72, v73
	v_mov_b32_e32 v73, v72
	s_nop 1
	v_permlane32_swap_b32_e32 v72, v73
	v_max_f32_e32 v74, v72, v73
	v_cmp_lt_f32_e64 s[70:71], s80, v74
	v_cmp_lt_f32_e64 s[72:73], s77, v74
	s_and_b64 s[70:71], s[70:71], s[68:69]
	s_andn2_b64 s[72:73], s[72:73], s[68:69]
	s_or_b64 s[70:71], s[70:71], s[72:73]
	s_cmp_lg_u64 s[70:71], 0
	s_cbranch_scc0 .Lmla_bar1
	v_add_f32_e32 v72, v198, v74
	v_cndmask_b32_e64 v75, 0, v74, s[70:71]
	v_cndmask_b32_e64 v208, v211, v72, s[70:71]
	v_sub_f32_e32 v72, v211, v208
	v_exp_f32_e32 v72, v72
	v_mov_b32_e32 v211, v208
	v_cndmask_b32_e64 v209, 1.0, v72, s[70:71]
	v_mul_f32_e32 v164, v164, v209
	v_mul_f32_e32 v84, v84, v209
	v_mul_f32_e32 v85, v85, v209
	v_mul_f32_e32 v86, v86, v209
	v_mul_f32_e32 v87, v87, v209
	v_mul_f32_e32 v76, v76, v209
	v_mul_f32_e32 v77, v77, v209
	v_mul_f32_e32 v78, v78, v209
	v_mul_f32_e32 v79, v79, v209
	v_mul_f32_e32 v80, v80, v209
	v_mul_f32_e32 v81, v81, v209
	v_mul_f32_e32 v82, v82, v209
	v_mul_f32_e32 v83, v83, v209
	v_mul_f32_e32 v56, v56, v209
	v_mul_f32_e32 v57, v57, v209
	v_mul_f32_e32 v58, v58, v209
	v_mul_f32_e32 v59, v59, v209
	v_sub_f32_e32 v116, v116, v75
	v_sub_f32_e32 v117, v117, v75
	v_sub_f32_e32 v118, v118, v75
	v_sub_f32_e32 v119, v119, v75
	v_sub_f32_e32 v120, v120, v75
	v_sub_f32_e32 v121, v121, v75
	v_sub_f32_e32 v122, v122, v75
	v_sub_f32_e32 v123, v123, v75
	v_sub_f32_e32 v124, v124, v75
	v_sub_f32_e32 v125, v125, v75
	v_sub_f32_e32 v126, v126, v75
	v_sub_f32_e32 v127, v127, v75
	v_sub_f32_e32 v128, v128, v75
	v_sub_f32_e32 v129, v129, v75
	v_sub_f32_e32 v130, v130, v75
	v_sub_f32_e32 v131, v131, v75
	v_cmp_lt_f32_e64 s[68:69], s77, v211
	s_nop 1
	v_cndmask_b32_e64 v198, 0, v211, s[68:69]
	s_and_b64 s[64:65], s[66:67], s[68:69]
	v_sub_f32_e32 v252, 0, v198
	v_mov_b32_e32 v253, v252
	v_mov_b32_e32 v254, v252
	v_mov_b32_e32 v255, v252
	s_branch .Lmla_bar1
